# v19 + grid barrier: the block arriving 8th-from-last on its XCD issues an early L2 write-back (buffer_wbl2 sc1) while it waits, so the leader's release fence finds less dirty data
# baseline (speedup 1.0000x reference)
.LBB0_264:
	global_atomic_add v3, v[64:65], v105, off sc0
	v_cvt_f32_u32_e32 v1, v2
	v_sub_u32_e32 v4, 0, v2
	v_rcp_iflag_f32_e32 v1, v1
	s_nop 0
	v_mul_f32_e32 v1, 0x4f7ffffe, v1
	v_cvt_u32_f32_e32 v1, v1
	v_mul_lo_u32 v4, v4, v1
	v_mul_hi_u32 v4, v1, v4
	v_add_u32_e32 v1, v1, v4
	s_waitcnt vmcnt(0)
	v_mul_hi_u32 v1, v3, v1
	v_mul_lo_u32 v4, v1, v2
	v_sub_u32_e32 v4, v3, v4
	v_add_u32_e32 v5, 1, v1
	v_cmp_ge_u32_e32 vcc, v4, v2
	v_add_u32_e32 v3, 1, v3
	s_nop 0
	v_cndmask_b32_e32 v1, v1, v5, vcc
	v_sub_u32_e32 v5, v4, v2
	v_cndmask_b32_e32 v4, v4, v5, vcc
	v_add_u32_e32 v5, 1, v1
	v_cmp_ge_u32_e32 vcc, v4, v2
	s_nop 1
	v_cndmask_b32_e32 v1, v1, v5, vcc
	v_mul_lo_u32 v4, v2, v1
	v_add_u32_e32 v2, v4, v2
	v_cmp_ne_u32_e32 vcc, v3, v2
	s_and_saveexec_b64 s[0:1], vcc
	s_xor_b64 s[0:1], exec, s[0:1]
	s_cbranch_execz .LBB0_278
	v_add_u32_e32 v5, 7, v3
	v_cmp_eq_u32_e32 vcc, v5, v2
	s_nop 4
	s_cbranch_vccz .Lwbskip_14
	buffer_wbl2 sc1
	s_waitcnt vmcnt(0)
.Lwbskip_14:
	s_waitcnt lgkmcnt(0)
	global_load_dword v0, v[66:67], off sc1
	s_waitcnt vmcnt(0)
	v_cmp_eq_u32_e32 vcc, v0, v1
	s_and_saveexec_b64 s[24:25], vcc
	s_cbranch_execz .LBB0_277
	s_mov_b32 s6, 1
	s_mov_b64 s[36:37], 0
	s_branch .LBB0_268
